# ssd_unit2 unit prologue: conv-weight and bias loads issued together with the state loads
# speedup vs baseline: 1.0033x; 1.0033x over previous
.LBB0_262:
	v_mov_b32_e32 v35, v216
	s_ashr_i32 s1, s2, 4
	v_readfirstlane_b32 s0, v35
	s_ashr_i32 s3, s0, 8
	s_bfe_u32 s16, s0, 0x20006
	s_lshl_b32 s0, s2, 1
	s_and_b32 s0, s0, 30
	s_mov_b32 s33, s2
	s_add_i32 s2, s3, s0
	s_mul_i32 s3, s3, 0xb400
	s_add_i32 s90, s3, 0
	s_lshl_b32 s3, s1, 5
	s_ashr_i32 s4, s2, 4
	s_add_i32 s6, s2, s3
	s_ashr_i32 s5, s4, 31
	s_ashr_i32 s7, s6, 31
	s_ashr_i32 s0, s2, 3
	s_lshl_b64 s[4:5], s[4:5], 25
	s_lshl_b64 s[6:7], s[6:7], 15
	s_add_u32 s6, s88, s6
	v_readlane_b32 s3, v254, 44
	s_addc_u32 s7, s89, s7
	s_add_i32 s8, s2, s3
	s_ashr_i32 s9, s8, 31
	v_readlane_b32 s36, v249, 56
	s_lshl_b64 s[8:9], s[8:9], 2
	v_readlane_b32 s40, v249, 60
	v_readlane_b32 s41, v249, 61
	s_add_u32 s10, s40, s8
	v_readlane_b32 s42, v249, 62
	s_addc_u32 s11, s41, s9
	v_readlane_b32 s43, v249, 63
	s_add_u32 s12, s42, s8
	v_and_b32_e32 v34, 63, v35
	v_readlane_b32 s44, v250, 0
	s_addc_u32 s13, s43, s9
	v_lshlrev_b32_e32 v0, 4, v34
	v_readlane_b32 s45, v250, 1
	s_add_u32 s8, s44, s8
	v_lshl_or_b32 v14, s16, 13, v0
	s_addc_u32 s9, s45, s9
	s_lshl_b32 s3, s16, 1
	global_load_dwordx4 v[6:9], v14, s[6:7]
	s_waitcnt lgkmcnt(0)
	global_load_dwordx4 v[2:5], v14, s[6:7] offset:1024
	s_or_b32 s3, s3, 1
	global_load_dwordx4 v[10:13], v14, s[6:7] offset:2048
	v_lshl_or_b32 v0, s3, 12, v0
	global_load_dwordx4 v[14:17], v14, s[6:7] offset:3072
	v_lshl_or_b32 v38, s2, 6, v34
	global_load_dword v37, v1, s[12:13]
	global_load_dwordx4 v[30:33], v0, s[6:7]
	global_load_dwordx4 v[18:21], v0, s[6:7] offset:1024
	global_load_dwordx4 v[26:29], v0, s[6:7] offset:2048
	global_load_dwordx4 v[22:25], v0, s[6:7] offset:3072
	v_ashrrev_i32_e32 v39, 31, v38
	v_readlane_b32 s18, v254, 45
	v_bfe_u32 v54, v35, 4, 2
	v_lshlrev_b64 v[38:39], 2, v[38:39]
	v_readlane_b32 s19, v254, 46
	v_lshlrev_b32_e32 v66, 3, v54
	s_movk_i32 s7, 0x3000
	v_lshl_add_u64 v[40:41], s[18:19], 0, v[38:39]
	v_and_b32_e32 v36, 15, v35
	v_add_u32_e32 v55, s90, v66
	v_add_co_u32_e32 v42, vcc, s7, v40
	v_mul_u32_u24_e32 v94, 0x110, v36
	v_lshl_add_u32 v95, s16, 6, v55
	s_movk_i32 s12, 0x110
	v_addc_co_u32_e32 v43, vcc, 0, v41, vcc
	s_movk_i32 s7, 0x6000
	s_lshl_b32 s3, s3, 5
	v_mad_u32_u24 v0, v36, s12, v95
	v_add_co_u32_e32 v44, vcc, s7, v40
	v_add3_u32 v56, v55, s3, v94
	s_add_u32 s3, s82, s4
	v_addc_co_u32_e32 v45, vcc, 0, v41, vcc
	global_load_dword v96, v1, s[8:9]
	global_load_dword v97, v1, s[10:11]
	v_add_co_u32_e32 v58, vcc, 0x9000, v40
	v_readlane_b32 s98, v254, 47
	v_readlane_b32 s99, v254, 48
	v_addc_co_u32_e32 v59, vcc, 0, v41, vcc
	s_nop 1
	v_lshl_add_u64 v[60:61], s[98:99], 0, v[38:39]
	global_load_dword v68, v[40:41], off
	global_load_dword v70, v[42:43], off
	global_load_dword v72, v[44:45], off
	global_load_dword v74, v[58:59], off
	global_load_dword v76, v[60:61], off
	s_addc_u32 s4, s83, s5
	s_lshl_b32 s5, s2, 7
	s_mov_b32 s7, 0x9000
	s_and_b32 s5, s5, 0x780
	v_readlane_b32 s11, v253, 55
	v_mov_b32_e32 v67, v1
	s_movk_i32 s10, 0x90
	v_readlane_b32 s37, v249, 57
	v_readlane_b32 s38, v249, 58
	v_readlane_b32 s39, v249, 59
	v_readlane_b32 s46, v250, 2
	v_readlane_b32 s47, v250, 3
	v_readlane_b32 s48, v250, 4
	v_readlane_b32 s49, v250, 5
	v_readlane_b32 s50, v250, 6
	v_readlane_b32 s51, v250, 7
	s_mov_b32 s6, 0
	s_waitcnt vmcnt(15)
	v_cvt_pk_bf16_f32 v46, v6, v7
	v_cvt_pk_bf16_f32 v47, v8, v9
	s_waitcnt vmcnt(14)
	v_cvt_pk_bf16_f32 v48, v2, v3
	v_cvt_pk_bf16_f32 v49, v4, v5
	s_waitcnt vmcnt(13)
	v_cvt_pk_bf16_f32 v50, v10, v11
	v_cvt_pk_bf16_f32 v51, v12, v13
	s_waitcnt vmcnt(12)
	v_cvt_pk_bf16_f32 v52, v14, v15
	v_cvt_pk_bf16_f32 v53, v16, v17
	ds_write_b64 v0, v[46:47] offset:28672
	ds_write_b64 v0, v[48:49] offset:33024
	ds_write_b64 v0, v[50:51] offset:37376
	ds_write_b64 v0, v[52:53] offset:41728
	s_waitcnt vmcnt(10)
	v_cvt_pk_bf16_f32 v46, v30, v31
	v_cvt_pk_bf16_f32 v47, v32, v33
	s_waitcnt vmcnt(9)
	v_cvt_pk_bf16_f32 v48, v18, v19
	v_cvt_pk_bf16_f32 v49, v20, v21
	s_waitcnt vmcnt(8)
	v_cvt_pk_bf16_f32 v50, v26, v27
	v_cvt_pk_bf16_f32 v51, v28, v29
	s_waitcnt vmcnt(7)
	v_cvt_pk_bf16_f32 v52, v22, v23
	v_cvt_pk_bf16_f32 v53, v24, v25
	ds_write_b64 v56, v[46:47] offset:28672
	ds_write_b64 v56, v[48:49] offset:33024
	ds_write_b64 v56, v[50:51] offset:37376
	ds_write_b64 v56, v[52:53] offset:41728
	v_add_co_u32_e32 v46, vcc, s7, v40
	s_lshl_b32 s7, s1, 8
	s_add_u32 s8, s3, s5
	s_addc_u32 s9, s4, 0
	v_readlane_b32 s4, v254, 47
	v_readlane_b32 s5, v254, 48
	v_addc_co_u32_e32 v47, vcc, 0, v41, vcc
	s_nop 0
	v_lshl_add_u64 v[38:39], s[4:5], 0, v[38:39]
	s_cmp_eq_u32 s16, 0
	v_mul_f32_e32 v0, 0x3fb8aa3b, v37
	s_cselect_b64 s[4:5], -1, 0
	v_readlane_b32 s1, v253, 54
	v_exp_f32_e32 v98, v0
	v_writelane_b32 v254, s4, 49
	s_cmp_lg_u32 s16, 0
	v_lshlrev_b32_e32 v0, 1, v34
	v_mov_b32_e32 v42, s1
	v_readlane_b32 s3, v253, 56
	s_mul_i32 s1, s16, 0x1100
	v_writelane_b32 v254, s5, 50
	s_cselect_b64 s[92:93], -1, 0
	v_lshl_add_u64 v[38:39], s[8:9], 0, v[0:1]
	s_mov_b64 s[4:5], 0x4000000
	s_lshl_b32 s14, s0, 7
	v_mov_b32_e32 v43, s3
	s_add_i32 s1, s3, s1
	s_ashr_i32 s3, s2, 31
	v_lshl_add_u64 v[78:79], v[38:39], 0, s[4:5]
	s_ashr_i32 s15, s14, 31
	s_lshl_b32 s17, s16, 4
	s_lshl_b64 s[2:3], s[2:3], 2
	v_readlane_b32 s4, v250, 20
	v_readlane_b32 s5, v250, 21
	s_add_u32 s2, s4, s2
	s_addc_u32 s3, s5, s3
	v_writelane_b32 v254, s2, 51
	v_cmp_eq_u32_e64 s[4:5], 0, v34
	v_mov_b32_e32 v47, s1
	v_writelane_b32 v254, s3, 52
	v_cmp_eq_u32_e64 s[2:3], 63, v34
	s_mul_i32 s1, s16, 0x900
	s_add_i32 s1, s90, s1
	v_writelane_b32 v254, s2, 53
	v_mov_b32_e32 v50, s1
	s_ashr_i32 s1, s0, 31
	v_writelane_b32 v254, s3, 54
	v_writelane_b32 v254, s4, 55
	s_lshl_b64 s[0:1], s[0:1], 2
	s_add_u32 s2, s20, s0
	v_writelane_b32 v254, s5, 56
	v_cmp_gt_u32_e64 s[4:5], 2, v34
	v_bfe_u32 v37, v35, 6, 2
	v_lshlrev_b32_e32 v44, 2, v54
	v_writelane_b32 v254, s4, 57
	v_and_b32_e32 v45, 48, v35
	v_mul_u32_u24_e32 v49, 0x90, v36
	v_writelane_b32 v254, s5, 58
	v_cmp_gt_u32_e64 s[4:5], 4, v34
	s_addc_u32 s3, s21, s1
	s_lshl_b32 s0, s16, 5
	v_writelane_b32 v254, s4, 59
	v_lshlrev_b32_e32 v40, 4, v37
	v_mov_b32_e32 v38, s90
	v_writelane_b32 v254, s5, 60
	v_cmp_gt_u32_e64 s[4:5], 8, v34
	v_lshlrev_b32_e32 v41, 5, v37
	v_mad_u32_u24 v101, v34, s12, v43
	v_writelane_b32 v254, s4, 61
	v_or_b32_e32 v43, s17, v36
	v_lshl_add_u64 v[80:81], s[8:9], 0, v[66:67]
	v_add3_u32 v67, s11, v49, v45
	v_writelane_b32 v254, s5, 62
	v_cmp_gt_u32_e64 s[4:5], 32, v34
	v_lshl_add_u32 v106, v37, 6, s90
	v_ashrrev_i32_e32 v37, 6, v35
	v_add_u32_e32 v35, 0x200, v35
	v_or_b32_e32 v49, 1, v44
	s_cmp_gt_u32 s16, 1
	v_mad_u32_u24 v39, v34, s10, v38
	v_add_u32_e32 v0, s11, v0
	v_mad_u32_u24 v103, v43, s10, v38
	v_mad_u32_u24 v46, v36, s12, v38
	v_mad_u32_u24 v38, v36, s10, v38
	v_mad_u32_u24 v50, v36, s10, v50
	v_writelane_b32 v254, s4, 63
	s_movk_i32 s1, 0x480
	v_ashrrev_i32_e32 v35, 6, v35
	v_cmp_eq_u32_e64 s[26:27], v49, v43
	v_or_b32_e32 v49, 2, v44
	s_cselect_b64 s[10:11], -1, 0
	s_cmp_eq_u32 s16, 3
	v_mad_u32_u24 v100, v34, s12, v42
	v_mad_u32_u24 v47, v36, s12, v47
	v_mad_u32_u24 v42, v36, s12, v42
	v_writelane_b32 v255, s5, 0
	v_lshlrev_b32_e32 v82, 3, v37
	v_lshlrev_b32_e32 v107, 4, v37
	v_mul_lo_u32 v37, v37, s1
	v_lshlrev_b32_e32 v84, 3, v35
	v_lshlrev_b32_e32 v108, 4, v35
	v_mul_lo_u32 v35, v35, s1
	v_cmp_le_u32_e64 s[28:29], v49, v43
	v_cmp_eq_u32_e64 s[30:31], v49, v43
	v_or_b32_e32 v49, 3, v44
	s_cselect_b64 s[12:13], -1, 0
	s_or_b32 s5, s0, 16
	s_lshl_b64 s[0:1], s[14:15], 1
	v_cmp_le_u32_e64 s[34:35], v49, v43
	v_cmp_eq_u32_e64 s[36:37], v49, v43
	v_or_b32_e32 v49, 16, v44
	s_add_u32 s14, s60, s0
	v_or_b32_e32 v56, 32, v44
	v_or_b32_e32 v61, 48, v44
	v_mul_i32_i24_e32 v48, 0xffffff74, v34
	v_cmp_le_u32_e64 s[20:21], v44, v43
	v_cmp_eq_u32_e64 s[22:23], v44, v43
	v_cmp_lt_u32_e64 s[24:25], v44, v43
	s_addc_u32 s15, s61, s1
	v_or_b32_e32 v51, 17, v44
	v_or_b32_e32 v52, 18, v44
	v_or_b32_e32 v53, 19, v44
	v_lshlrev_b32_e32 v54, 1, v49
	v_or_b32_e32 v57, 33, v44
	v_or_b32_e32 v58, 34, v44
	v_or_b32_e32 v59, 35, v44
	v_lshlrev_b32_e32 v60, 1, v56
	v_or_b32_e32 v62, 49, v44
	v_or_b32_e32 v63, 50, v44
	v_or_b32_e32 v44, 51, v44
	v_lshlrev_b32_e32 v64, 1, v61
	v_lshl_add_u32 v55, s5, 1, v55
	s_or_b32 s0, s7, s17
	v_add_u32_e32 v99, -3, v40
	v_lshl_add_u32 v102, v43, 2, s90
	v_cmp_gt_u32_e64 s[8:9], 16, v34
	v_add_u32_e32 v104, -2, v40
	v_add_u32_e32 v105, -1, v40
	v_ashrrev_i32_e32 v83, 31, v82
	v_ashrrev_i32_e32 v85, 31, v84
	v_add_u32_e32 v109, s90, v45
	v_cmp_le_u32_e64 s[38:39], v49, v43
	s_mul_i32 s4, s16, 0x1200
	s_mulk_i32 s5, 0x90
	s_waitcnt vmcnt(0)
	v_mov_b32_e32 v77, v76
	v_mov_b32_e32 v69, v68
	v_mov_b32_e32 v71, v70
	v_mov_b32_e32 v73, v72
	v_mov_b32_e32 v75, v74
	v_or_b32_e32 v110, s7, v34
	v_or_b32_e32 v111, s7, v40
	v_or_b32_e32 v112, s0, v36
	v_add_u32_e32 v113, v39, v48
	v_add_u32_e32 v114, v39, v41
	v_add_u32_e32 v115, v0, v37
	v_add_u32_e32 v116, v0, v35
	v_add_u32_e32 v117, v103, v54
	v_add_u32_e32 v118, v103, v60
	v_add_u32_e32 v119, v103, v64
	v_add_u32_e32 v120, v50, v45
	v_add_u32_e32 v121, v55, v94
	v_add_u32_e32 v122, v42, v45
	v_add_u32_e32 v123, v47, v45
	v_add_u32_e32 v124, v46, v45
	v_add_u32_e32 v125, v38, v45
	v_cmp_eq_u32_e64 s[40:41], v49, v43
	v_cmp_le_u32_e64 s[42:43], v51, v43
	v_cmp_eq_u32_e64 s[44:45], v51, v43
	v_cmp_le_u32_e64 s[46:47], v52, v43
	v_cmp_eq_u32_e64 s[48:49], v52, v43
	v_cmp_le_u32_e64 s[50:51], v53, v43
	v_cmp_eq_u32_e64 s[52:53], v53, v43
	v_cmp_le_u32_e64 s[54:55], v56, v43
	v_cmp_eq_u32_e64 s[56:57], v56, v43
	v_cmp_le_u32_e64 s[58:59], v57, v43
	v_cmp_eq_u32_e64 s[60:61], v57, v43
	v_cmp_le_u32_e64 s[62:63], v58, v43
	v_cmp_eq_u32_e64 s[64:65], v58, v43
	v_cmp_le_u32_e64 s[66:67], v59, v43
	v_cmp_eq_u32_e64 s[68:69], v59, v43
	v_cmp_le_u32_e64 s[70:71], v61, v43
	v_cmp_eq_u32_e64 s[72:73], v61, v43
	v_cmp_le_u32_e64 s[74:75], v62, v43
	v_cmp_eq_u32_e64 s[76:77], v62, v43
	v_cmp_le_u32_e64 s[78:79], v63, v43
	v_cmp_eq_u32_e64 s[80:81], v63, v43
	v_cmp_le_u32_e64 s[82:83], v44, v43
	v_cmp_eq_u32_e64 s[84:85], v44, v43
	s_branch .LBB0_264
